# RWKV-7 prompt step block rewritten with packed f32 math (v_pk_mul/v_pk_fma) on top of the early-invalidate flat barrier
# speedup vs baseline: 1.0082x; 1.0034x over previous
.LBB0_433:
	s_or_b64 exec, exec, s[4:5]
	v_lshl_add_u32 v17, v34, 2, s84
	v_add3_u32 v18, s84, v91, v92
	v_add_u32_e32 v25, 0x5000, v18
	v_bfe_u32 v19, v34, 2, 2
	ds_read2_b32 v[236:237], v25 offset0:0 offset1:16
	ds_read_b128 v[164:167], v17 offset:12288
	ds_read_b128 v[156:159], v17 offset:4096
	ds_read_b128 v[168:171], v17 offset:16384
	ds_read_b128 v[160:163], v17 offset:8192
	ds_read_b128 v[152:155], v17
	ds_read_b128 v[188:191], v17 offset:12544
	ds_read_b128 v[180:183], v17 offset:4352
	ds_read_b128 v[192:195], v17 offset:16640
	ds_read_b128 v[184:187], v17 offset:8448
	ds_read_b128 v[176:179], v17 offset:256
	s_waitcnt lgkmcnt(0)
	v_pk_mul_f32 v[250:251], v[164:165], v[56:57]
	v_pk_mul_f32 v[20:21], v[156:157], v[236:237] op_sel_hi:[1,0]
	v_pk_fma_f32 v[250:251], v[166:167], v[58:59], v[250:251]
	v_pk_mul_f32 v[22:23], v[158:159], v[236:237] op_sel_hi:[1,0]
	v_add_f32_e32 v16, v250, v251
	ds_read2_b32 v[238:239], v25 offset0:32 offset1:48
	ds_read_b128 v[208:211], v17 offset:12800
	v_add_f32_dpp v16, v16, v16 row_ror:8 row_mask:0xf bank_mask:0xf bound_ctrl:1
	ds_read_b128 v[200:203], v17 offset:4608
	ds_read_b128 v[212:215], v17 offset:16896
	v_add_f32_dpp v16, v16, v16 row_ror:4 row_mask:0xf bank_mask:0xf bound_ctrl:1
	ds_read_b128 v[204:207], v17 offset:8704
	ds_read_b128 v[196:199], v17 offset:512
	v_add_f32_dpp v16, v16, v16 row_ror:2 row_mask:0xf bank_mask:0xf bound_ctrl:1
	ds_read_b128 v[228:231], v17 offset:13056
	ds_read_b128 v[220:223], v17 offset:4864
	v_add_f32_dpp v16, v16, v16 row_ror:1 row_mask:0xf bank_mask:0xf bound_ctrl:1
	v_pk_fma_f32 v[20:21], v[168:169], v[16:17], v[20:21] op_sel_hi:[1,0,1] neg_lo:[1,0,0] neg_hi:[1,0,0]
	v_pk_fma_f32 v[22:23], v[170:171], v[16:17], v[22:23] op_sel_hi:[1,0,1] neg_lo:[1,0,0] neg_hi:[1,0,0]
	v_pk_fma_f32 v[56:57], v[160:161], v[56:57], v[20:21]
	v_pk_fma_f32 v[58:59], v[162:163], v[58:59], v[22:23]
	v_pk_mul_f32 v[250:251], v[188:189], v[56:57]
	v_pk_mul_f32 v[20:21], v[180:181], v[236:237] op_sel:[0,1]
	v_pk_fma_f32 v[250:251], v[190:191], v[58:59], v[250:251]
	v_pk_mul_f32 v[22:23], v[182:183], v[236:237] op_sel:[0,1]
	v_add_f32_e32 v16, v250, v251
	v_pk_mul_f32 v[252:253], v[152:153], v[56:57]
	ds_read_b128 v[232:235], v17 offset:17152
	v_add_f32_dpp v16, v16, v16 row_ror:8 row_mask:0xf bank_mask:0xf bound_ctrl:1
	v_pk_fma_f32 v[252:253], v[154:155], v[58:59], v[252:253]
	ds_read_b128 v[224:227], v17 offset:8960
	v_add_f32_dpp v16, v16, v16 row_ror:4 row_mask:0xf bank_mask:0xf bound_ctrl:1
	v_add_f32_e32 v240, v252, v253
	ds_read_b128 v[216:219], v17 offset:768
	v_add_f32_dpp v16, v16, v16 row_ror:2 row_mask:0xf bank_mask:0xf bound_ctrl:1
	s_nop 0
	s_nop 0
	v_add_f32_dpp v16, v16, v16 row_ror:1 row_mask:0xf bank_mask:0xf bound_ctrl:1
	v_pk_fma_f32 v[20:21], v[192:193], v[16:17], v[20:21] op_sel_hi:[1,0,1] neg_lo:[1,0,0] neg_hi:[1,0,0]
	v_pk_fma_f32 v[22:23], v[194:195], v[16:17], v[22:23] op_sel_hi:[1,0,1] neg_lo:[1,0,0] neg_hi:[1,0,0]
	v_pk_fma_f32 v[56:57], v[184:185], v[56:57], v[20:21]
	v_pk_fma_f32 v[58:59], v[186:187], v[58:59], v[22:23]
	s_waitcnt lgkmcnt(0)
	v_pk_mul_f32 v[250:251], v[208:209], v[56:57]
	v_pk_mul_f32 v[20:21], v[200:201], v[238:239] op_sel_hi:[1,0]
	v_pk_fma_f32 v[250:251], v[210:211], v[58:59], v[250:251]
	v_pk_mul_f32 v[22:23], v[202:203], v[238:239] op_sel_hi:[1,0]
	v_add_f32_e32 v16, v250, v251
	v_pk_mul_f32 v[252:253], v[176:177], v[56:57]
	s_nop 0
	v_add_f32_dpp v16, v16, v16 row_ror:8 row_mask:0xf bank_mask:0xf bound_ctrl:1
	v_pk_fma_f32 v[252:253], v[178:179], v[58:59], v[252:253]
	ds_read2_b32 v[236:237], v25 offset0:64 offset1:80
	v_add_f32_dpp v16, v16, v16 row_ror:4 row_mask:0xf bank_mask:0xf bound_ctrl:1
	v_add_f32_e32 v241, v252, v253
	ds_read_b128 v[164:167], v17 offset:13312
	v_add_f32_dpp v16, v16, v16 row_ror:2 row_mask:0xf bank_mask:0xf bound_ctrl:1
	ds_read_b128 v[156:159], v17 offset:5120
	ds_read_b128 v[168:171], v17 offset:17408
	v_add_f32_dpp v16, v16, v16 row_ror:1 row_mask:0xf bank_mask:0xf bound_ctrl:1
	v_pk_fma_f32 v[20:21], v[212:213], v[16:17], v[20:21] op_sel_hi:[1,0,1] neg_lo:[1,0,0] neg_hi:[1,0,0]
	v_pk_fma_f32 v[22:23], v[214:215], v[16:17], v[22:23] op_sel_hi:[1,0,1] neg_lo:[1,0,0] neg_hi:[1,0,0]
	v_pk_fma_f32 v[56:57], v[204:205], v[56:57], v[20:21]
	v_pk_fma_f32 v[58:59], v[206:207], v[58:59], v[22:23]
	v_pk_mul_f32 v[250:251], v[228:229], v[56:57]
	v_pk_mul_f32 v[20:21], v[220:221], v[238:239] op_sel:[0,1]
	v_pk_fma_f32 v[250:251], v[230:231], v[58:59], v[250:251]
	v_pk_mul_f32 v[22:23], v[222:223], v[238:239] op_sel:[0,1]
	v_add_f32_e32 v16, v250, v251
	v_pk_mul_f32 v[252:253], v[196:197], v[56:57]
	ds_read_b128 v[160:163], v17 offset:9216
	v_add_f32_dpp v16, v16, v16 row_ror:8 row_mask:0xf bank_mask:0xf bound_ctrl:1
	v_pk_fma_f32 v[252:253], v[198:199], v[58:59], v[252:253]
	ds_read_b128 v[152:155], v17 offset:1024
	v_add_f32_dpp v16, v16, v16 row_ror:4 row_mask:0xf bank_mask:0xf bound_ctrl:1
	v_add_f32_e32 v242, v252, v253
	ds_read_b128 v[188:191], v17 offset:13568
	v_add_f32_dpp v16, v16, v16 row_ror:2 row_mask:0xf bank_mask:0xf bound_ctrl:1
	ds_read_b128 v[180:183], v17 offset:5376
	ds_read_b128 v[192:195], v17 offset:17664
	v_add_f32_dpp v16, v16, v16 row_ror:1 row_mask:0xf bank_mask:0xf bound_ctrl:1
	v_pk_fma_f32 v[20:21], v[232:233], v[16:17], v[20:21] op_sel_hi:[1,0,1] neg_lo:[1,0,0] neg_hi:[1,0,0]
	v_pk_fma_f32 v[22:23], v[234:235], v[16:17], v[22:23] op_sel_hi:[1,0,1] neg_lo:[1,0,0] neg_hi:[1,0,0]
	v_pk_fma_f32 v[56:57], v[224:225], v[56:57], v[20:21]
	v_pk_fma_f32 v[58:59], v[226:227], v[58:59], v[22:23]
	ds_read_b128 v[184:187], v17 offset:9472
	ds_read_b128 v[176:179], v17 offset:1280
	s_waitcnt lgkmcnt(0)
	v_pk_mul_f32 v[250:251], v[164:165], v[56:57]
	v_pk_mul_f32 v[20:21], v[156:157], v[236:237] op_sel_hi:[1,0]
	v_pk_fma_f32 v[250:251], v[166:167], v[58:59], v[250:251]
	v_pk_mul_f32 v[22:23], v[158:159], v[236:237] op_sel_hi:[1,0]
	v_add_f32_e32 v16, v250, v251
	v_pk_mul_f32 v[252:253], v[216:217], v[56:57]
	s_nop 0
	v_add_f32_dpp v16, v16, v16 row_ror:8 row_mask:0xf bank_mask:0xf bound_ctrl:1
	v_pk_fma_f32 v[252:253], v[218:219], v[58:59], v[252:253]
	ds_read2_b32 v[238:239], v25 offset0:96 offset1:112
	v_add_f32_dpp v16, v16, v16 row_ror:4 row_mask:0xf bank_mask:0xf bound_ctrl:1
	v_add_f32_e32 v243, v252, v253
	ds_read_b128 v[208:211], v17 offset:13824
	v_add_f32_dpp v16, v16, v16 row_ror:2 row_mask:0xf bank_mask:0xf bound_ctrl:1
	ds_read_b128 v[200:203], v17 offset:5632
	ds_read_b128 v[212:215], v17 offset:17920
	v_add_f32_dpp v16, v16, v16 row_ror:1 row_mask:0xf bank_mask:0xf bound_ctrl:1
	v_pk_fma_f32 v[20:21], v[168:169], v[16:17], v[20:21] op_sel_hi:[1,0,1] neg_lo:[1,0,0] neg_hi:[1,0,0]
	v_pk_fma_f32 v[22:23], v[170:171], v[16:17], v[22:23] op_sel_hi:[1,0,1] neg_lo:[1,0,0] neg_hi:[1,0,0]
	v_pk_fma_f32 v[56:57], v[160:161], v[56:57], v[20:21]
	v_pk_fma_f32 v[58:59], v[162:163], v[58:59], v[22:23]
	v_pk_mul_f32 v[250:251], v[188:189], v[56:57]
	v_pk_mul_f32 v[20:21], v[180:181], v[236:237] op_sel:[0,1]
	v_pk_fma_f32 v[250:251], v[190:191], v[58:59], v[250:251]
	v_pk_mul_f32 v[22:23], v[182:183], v[236:237] op_sel:[0,1]
	v_add_f32_e32 v16, v250, v251
	v_pk_mul_f32 v[252:253], v[152:153], v[56:57]
	ds_read_b128 v[204:207], v17 offset:9728
	v_add_f32_dpp v16, v16, v16 row_ror:8 row_mask:0xf bank_mask:0xf bound_ctrl:1
	v_pk_fma_f32 v[252:253], v[154:155], v[58:59], v[252:253]
	ds_read_b128 v[196:199], v17 offset:1536
	v_add_f32_dpp v16, v16, v16 row_ror:4 row_mask:0xf bank_mask:0xf bound_ctrl:1
	v_add_f32_e32 v244, v252, v253
	ds_read_b128 v[228:231], v17 offset:14080
	v_add_f32_dpp v16, v16, v16 row_ror:2 row_mask:0xf bank_mask:0xf bound_ctrl:1
	ds_read_b128 v[220:223], v17 offset:5888
	ds_read_b128 v[232:235], v17 offset:18176
	v_add_f32_dpp v16, v16, v16 row_ror:1 row_mask:0xf bank_mask:0xf bound_ctrl:1
	v_pk_fma_f32 v[20:21], v[192:193], v[16:17], v[20:21] op_sel_hi:[1,0,1] neg_lo:[1,0,0] neg_hi:[1,0,0]
	v_pk_fma_f32 v[22:23], v[194:195], v[16:17], v[22:23] op_sel_hi:[1,0,1] neg_lo:[1,0,0] neg_hi:[1,0,0]
	v_pk_fma_f32 v[56:57], v[184:185], v[56:57], v[20:21]
	v_pk_fma_f32 v[58:59], v[186:187], v[58:59], v[22:23]
	ds_read_b128 v[224:227], v17 offset:9984
	ds_read_b128 v[216:219], v17 offset:1792
	s_waitcnt lgkmcnt(0)
	v_pk_mul_f32 v[250:251], v[208:209], v[56:57]
	v_pk_mul_f32 v[20:21], v[200:201], v[238:239] op_sel_hi:[1,0]
	v_pk_fma_f32 v[250:251], v[210:211], v[58:59], v[250:251]
	v_pk_mul_f32 v[22:23], v[202:203], v[238:239] op_sel_hi:[1,0]
	v_add_f32_e32 v16, v250, v251
	v_pk_mul_f32 v[252:253], v[176:177], v[56:57]
	s_nop 0
	v_add_f32_dpp v16, v16, v16 row_ror:8 row_mask:0xf bank_mask:0xf bound_ctrl:1
	v_pk_fma_f32 v[252:253], v[178:179], v[58:59], v[252:253]
	ds_read2_b32 v[236:237], v25 offset0:128 offset1:144
	v_add_f32_dpp v16, v16, v16 row_ror:4 row_mask:0xf bank_mask:0xf bound_ctrl:1
	v_add_f32_e32 v245, v252, v253
	ds_read_b128 v[164:167], v17 offset:14336
	v_add_f32_dpp v16, v16, v16 row_ror:2 row_mask:0xf bank_mask:0xf bound_ctrl:1
	ds_read_b128 v[156:159], v17 offset:6144
	ds_read_b128 v[168:171], v17 offset:18432
	v_add_f32_dpp v16, v16, v16 row_ror:1 row_mask:0xf bank_mask:0xf bound_ctrl:1
	v_pk_fma_f32 v[20:21], v[212:213], v[16:17], v[20:21] op_sel_hi:[1,0,1] neg_lo:[1,0,0] neg_hi:[1,0,0]
	v_pk_fma_f32 v[22:23], v[214:215], v[16:17], v[22:23] op_sel_hi:[1,0,1] neg_lo:[1,0,0] neg_hi:[1,0,0]
	v_pk_fma_f32 v[56:57], v[204:205], v[56:57], v[20:21]
	v_pk_fma_f32 v[58:59], v[206:207], v[58:59], v[22:23]
	v_pk_mul_f32 v[250:251], v[228:229], v[56:57]
	v_pk_mul_f32 v[20:21], v[220:221], v[238:239] op_sel:[0,1]
	v_pk_fma_f32 v[250:251], v[230:231], v[58:59], v[250:251]
	v_pk_mul_f32 v[22:23], v[222:223], v[238:239] op_sel:[0,1]
	v_add_f32_e32 v16, v250, v251
	v_pk_mul_f32 v[252:253], v[196:197], v[56:57]
	ds_read_b128 v[160:163], v17 offset:10240
	v_add_f32_dpp v16, v16, v16 row_ror:8 row_mask:0xf bank_mask:0xf bound_ctrl:1
	v_pk_fma_f32 v[252:253], v[198:199], v[58:59], v[252:253]
	ds_read_b128 v[152:155], v17 offset:2048
	v_add_f32_dpp v16, v16, v16 row_ror:4 row_mask:0xf bank_mask:0xf bound_ctrl:1
	v_add_f32_e32 v246, v252, v253
	ds_read_b128 v[188:191], v17 offset:14592
	v_add_f32_dpp v16, v16, v16 row_ror:2 row_mask:0xf bank_mask:0xf bound_ctrl:1
	ds_read_b128 v[180:183], v17 offset:6400
	ds_read_b128 v[192:195], v17 offset:18688
	v_add_f32_dpp v16, v16, v16 row_ror:1 row_mask:0xf bank_mask:0xf bound_ctrl:1
	v_pk_fma_f32 v[20:21], v[232:233], v[16:17], v[20:21] op_sel_hi:[1,0,1] neg_lo:[1,0,0] neg_hi:[1,0,0]
	v_pk_fma_f32 v[22:23], v[234:235], v[16:17], v[22:23] op_sel_hi:[1,0,1] neg_lo:[1,0,0] neg_hi:[1,0,0]
	v_pk_fma_f32 v[56:57], v[224:225], v[56:57], v[20:21]
	v_pk_fma_f32 v[58:59], v[226:227], v[58:59], v[22:23]
	ds_read_b128 v[184:187], v17 offset:10496
	ds_read_b128 v[176:179], v17 offset:2304
	s_waitcnt lgkmcnt(0)
	v_pk_mul_f32 v[250:251], v[164:165], v[56:57]
	v_pk_mul_f32 v[20:21], v[156:157], v[236:237] op_sel_hi:[1,0]
	v_pk_fma_f32 v[250:251], v[166:167], v[58:59], v[250:251]
	v_pk_mul_f32 v[22:23], v[158:159], v[236:237] op_sel_hi:[1,0]
	v_add_f32_e32 v16, v250, v251
	v_pk_mul_f32 v[252:253], v[216:217], v[56:57]
	s_nop 0
	v_add_f32_dpp v16, v16, v16 row_ror:8 row_mask:0xf bank_mask:0xf bound_ctrl:1
	v_pk_fma_f32 v[252:253], v[218:219], v[58:59], v[252:253]
	ds_read2_b32 v[238:239], v25 offset0:160 offset1:176
	v_add_f32_dpp v16, v16, v16 row_ror:4 row_mask:0xf bank_mask:0xf bound_ctrl:1
	v_add_f32_e32 v247, v252, v253
	ds_read_b128 v[208:211], v17 offset:14848
	v_add_f32_dpp v16, v16, v16 row_ror:2 row_mask:0xf bank_mask:0xf bound_ctrl:1
	ds_read_b128 v[200:203], v17 offset:6656
	ds_read_b128 v[212:215], v17 offset:18944
	v_add_f32_dpp v16, v16, v16 row_ror:1 row_mask:0xf bank_mask:0xf bound_ctrl:1
	v_pk_fma_f32 v[20:21], v[168:169], v[16:17], v[20:21] op_sel_hi:[1,0,1] neg_lo:[1,0,0] neg_hi:[1,0,0]
	v_pk_fma_f32 v[22:23], v[170:171], v[16:17], v[22:23] op_sel_hi:[1,0,1] neg_lo:[1,0,0] neg_hi:[1,0,0]
	v_pk_fma_f32 v[56:57], v[160:161], v[56:57], v[20:21]
	v_pk_fma_f32 v[58:59], v[162:163], v[58:59], v[22:23]
	v_pk_mul_f32 v[250:251], v[188:189], v[56:57]
	v_pk_mul_f32 v[20:21], v[180:181], v[236:237] op_sel:[0,1]
	v_pk_fma_f32 v[250:251], v[190:191], v[58:59], v[250:251]
	v_pk_mul_f32 v[22:23], v[182:183], v[236:237] op_sel:[0,1]
	v_add_f32_e32 v16, v250, v251
	v_pk_mul_f32 v[252:253], v[152:153], v[56:57]
	ds_read_b128 v[204:207], v17 offset:10752
	v_add_f32_dpp v16, v16, v16 row_ror:8 row_mask:0xf bank_mask:0xf bound_ctrl:1
	v_pk_fma_f32 v[252:253], v[154:155], v[58:59], v[252:253]
	ds_read_b128 v[196:199], v17 offset:2560
	v_add_f32_dpp v16, v16, v16 row_ror:4 row_mask:0xf bank_mask:0xf bound_ctrl:1
	v_add_f32_e32 v248, v252, v253
	ds_read_b128 v[228:231], v17 offset:15104
	v_add_f32_dpp v16, v16, v16 row_ror:2 row_mask:0xf bank_mask:0xf bound_ctrl:1
	ds_read_b128 v[220:223], v17 offset:6912
	ds_read_b128 v[232:235], v17 offset:19200
	v_add_f32_dpp v16, v16, v16 row_ror:1 row_mask:0xf bank_mask:0xf bound_ctrl:1
	v_pk_fma_f32 v[20:21], v[192:193], v[16:17], v[20:21] op_sel_hi:[1,0,1] neg_lo:[1,0,0] neg_hi:[1,0,0]
	v_pk_fma_f32 v[22:23], v[194:195], v[16:17], v[22:23] op_sel_hi:[1,0,1] neg_lo:[1,0,0] neg_hi:[1,0,0]
	v_pk_fma_f32 v[56:57], v[184:185], v[56:57], v[20:21]
	v_pk_fma_f32 v[58:59], v[186:187], v[58:59], v[22:23]
	ds_read_b128 v[224:227], v17 offset:11008
	ds_read_b128 v[216:219], v17 offset:2816
	s_waitcnt lgkmcnt(0)
	v_pk_mul_f32 v[250:251], v[208:209], v[56:57]
	v_pk_mul_f32 v[20:21], v[200:201], v[238:239] op_sel_hi:[1,0]
	v_pk_fma_f32 v[250:251], v[210:211], v[58:59], v[250:251]
	v_pk_mul_f32 v[22:23], v[202:203], v[238:239] op_sel_hi:[1,0]
	v_add_f32_e32 v16, v250, v251
	v_pk_mul_f32 v[252:253], v[176:177], v[56:57]
	s_nop 0
	v_add_f32_dpp v16, v16, v16 row_ror:8 row_mask:0xf bank_mask:0xf bound_ctrl:1
	v_pk_fma_f32 v[252:253], v[178:179], v[58:59], v[252:253]
	ds_read2_b32 v[236:237], v25 offset0:192 offset1:208
	v_add_f32_dpp v16, v16, v16 row_ror:4 row_mask:0xf bank_mask:0xf bound_ctrl:1
	v_add_f32_e32 v249, v252, v253
	ds_read_b128 v[164:167], v17 offset:15360
	v_add_f32_dpp v16, v16, v16 row_ror:2 row_mask:0xf bank_mask:0xf bound_ctrl:1
	ds_read_b128 v[156:159], v17 offset:7168
	ds_read_b128 v[168:171], v17 offset:19456
	v_add_f32_dpp v16, v16, v16 row_ror:1 row_mask:0xf bank_mask:0xf bound_ctrl:1
	v_pk_fma_f32 v[20:21], v[212:213], v[16:17], v[20:21] op_sel_hi:[1,0,1] neg_lo:[1,0,0] neg_hi:[1,0,0]
	v_pk_fma_f32 v[22:23], v[214:215], v[16:17], v[22:23] op_sel_hi:[1,0,1] neg_lo:[1,0,0] neg_hi:[1,0,0]
	v_pk_fma_f32 v[56:57], v[204:205], v[56:57], v[20:21]
	v_pk_fma_f32 v[58:59], v[206:207], v[58:59], v[22:23]
	v_pk_mul_f32 v[250:251], v[228:229], v[56:57]
	v_pk_mul_f32 v[20:21], v[220:221], v[238:239] op_sel:[0,1]
	v_pk_fma_f32 v[250:251], v[230:231], v[58:59], v[250:251]
	v_pk_mul_f32 v[22:23], v[222:223], v[238:239] op_sel:[0,1]
	v_add_f32_e32 v16, v250, v251
	v_pk_mul_f32 v[252:253], v[196:197], v[56:57]
	ds_read_b128 v[160:163], v17 offset:11264
	v_add_f32_dpp v16, v16, v16 row_ror:8 row_mask:0xf bank_mask:0xf bound_ctrl:1
	v_pk_fma_f32 v[252:253], v[198:199], v[58:59], v[252:253]
	ds_read_b128 v[152:155], v17 offset:3072
	v_add_f32_dpp v16, v16, v16 row_ror:4 row_mask:0xf bank_mask:0xf bound_ctrl:1
	v_add_f32_e32 v150, v252, v253
	ds_read_b128 v[188:191], v17 offset:15616
	v_add_f32_dpp v16, v16, v16 row_ror:2 row_mask:0xf bank_mask:0xf bound_ctrl:1
	ds_read_b128 v[180:183], v17 offset:7424
	ds_read_b128 v[192:195], v17 offset:19712
	v_add_f32_dpp v16, v16, v16 row_ror:1 row_mask:0xf bank_mask:0xf bound_ctrl:1
	v_pk_fma_f32 v[20:21], v[232:233], v[16:17], v[20:21] op_sel_hi:[1,0,1] neg_lo:[1,0,0] neg_hi:[1,0,0]
	v_pk_fma_f32 v[22:23], v[234:235], v[16:17], v[22:23] op_sel_hi:[1,0,1] neg_lo:[1,0,0] neg_hi:[1,0,0]
	v_pk_fma_f32 v[56:57], v[224:225], v[56:57], v[20:21]
	v_pk_fma_f32 v[58:59], v[226:227], v[58:59], v[22:23]
	ds_read_b128 v[184:187], v17 offset:11520
	ds_read_b128 v[176:179], v17 offset:3328
	s_waitcnt lgkmcnt(0)
	v_pk_mul_f32 v[250:251], v[164:165], v[56:57]
	v_pk_mul_f32 v[20:21], v[156:157], v[236:237] op_sel_hi:[1,0]
	v_pk_fma_f32 v[250:251], v[166:167], v[58:59], v[250:251]
	v_pk_mul_f32 v[22:23], v[158:159], v[236:237] op_sel_hi:[1,0]
	v_add_f32_e32 v16, v250, v251
	v_pk_mul_f32 v[252:253], v[216:217], v[56:57]
	s_nop 0
	v_add_f32_dpp v16, v16, v16 row_ror:8 row_mask:0xf bank_mask:0xf bound_ctrl:1
	v_pk_fma_f32 v[252:253], v[218:219], v[58:59], v[252:253]
	ds_read2_b32 v[238:239], v25 offset0:224 offset1:240
	v_add_f32_dpp v16, v16, v16 row_ror:4 row_mask:0xf bank_mask:0xf bound_ctrl:1
	v_add_f32_e32 v151, v252, v253
	ds_read_b128 v[208:211], v17 offset:15872
	v_add_f32_dpp v16, v16, v16 row_ror:2 row_mask:0xf bank_mask:0xf bound_ctrl:1
	ds_read_b128 v[200:203], v17 offset:7680
	ds_read_b128 v[212:215], v17 offset:19968
	v_add_f32_dpp v16, v16, v16 row_ror:1 row_mask:0xf bank_mask:0xf bound_ctrl:1
	v_pk_fma_f32 v[20:21], v[168:169], v[16:17], v[20:21] op_sel_hi:[1,0,1] neg_lo:[1,0,0] neg_hi:[1,0,0]
	v_pk_fma_f32 v[22:23], v[170:171], v[16:17], v[22:23] op_sel_hi:[1,0,1] neg_lo:[1,0,0] neg_hi:[1,0,0]
	v_pk_fma_f32 v[56:57], v[160:161], v[56:57], v[20:21]
	v_pk_fma_f32 v[58:59], v[162:163], v[58:59], v[22:23]
	v_pk_mul_f32 v[250:251], v[188:189], v[56:57]
	v_pk_mul_f32 v[20:21], v[180:181], v[236:237] op_sel:[0,1]
	v_pk_fma_f32 v[250:251], v[190:191], v[58:59], v[250:251]
	v_pk_mul_f32 v[22:23], v[182:183], v[236:237] op_sel:[0,1]
	v_add_f32_e32 v16, v250, v251
	v_pk_mul_f32 v[252:253], v[152:153], v[56:57]
	ds_read_b128 v[204:207], v17 offset:11776
	v_add_f32_dpp v16, v16, v16 row_ror:8 row_mask:0xf bank_mask:0xf bound_ctrl:1
	v_pk_fma_f32 v[252:253], v[154:155], v[58:59], v[252:253]
	ds_read_b128 v[196:199], v17 offset:3584
	v_add_f32_dpp v16, v16, v16 row_ror:4 row_mask:0xf bank_mask:0xf bound_ctrl:1
	v_add_f32_e32 v26, v252, v253
	ds_read_b128 v[228:231], v17 offset:16128
	v_add_f32_dpp v16, v16, v16 row_ror:2 row_mask:0xf bank_mask:0xf bound_ctrl:1
	ds_read_b128 v[220:223], v17 offset:7936
	ds_read_b128 v[232:235], v17 offset:20224
	v_add_f32_dpp v16, v16, v16 row_ror:1 row_mask:0xf bank_mask:0xf bound_ctrl:1
	v_pk_fma_f32 v[20:21], v[192:193], v[16:17], v[20:21] op_sel_hi:[1,0,1] neg_lo:[1,0,0] neg_hi:[1,0,0]
	v_pk_fma_f32 v[22:23], v[194:195], v[16:17], v[22:23] op_sel_hi:[1,0,1] neg_lo:[1,0,0] neg_hi:[1,0,0]
	v_pk_fma_f32 v[56:57], v[184:185], v[56:57], v[20:21]
	v_pk_fma_f32 v[58:59], v[186:187], v[58:59], v[22:23]
	ds_read_b128 v[224:227], v17 offset:12032
	ds_read_b128 v[216:219], v17 offset:3840
	s_waitcnt lgkmcnt(0)
	v_pk_mul_f32 v[250:251], v[208:209], v[56:57]
	v_pk_mul_f32 v[20:21], v[200:201], v[238:239] op_sel_hi:[1,0]
	v_pk_fma_f32 v[250:251], v[210:211], v[58:59], v[250:251]
	v_pk_mul_f32 v[22:23], v[202:203], v[238:239] op_sel_hi:[1,0]
	v_add_f32_e32 v16, v250, v251
	v_pk_mul_f32 v[252:253], v[176:177], v[56:57]
	s_nop 0
	v_add_f32_dpp v16, v16, v16 row_ror:8 row_mask:0xf bank_mask:0xf bound_ctrl:1
	v_pk_fma_f32 v[252:253], v[178:179], v[58:59], v[252:253]
	s_nop 0
	v_add_f32_dpp v16, v16, v16 row_ror:4 row_mask:0xf bank_mask:0xf bound_ctrl:1
	v_add_f32_e32 v27, v252, v253
	s_nop 0
	v_add_f32_dpp v16, v16, v16 row_ror:2 row_mask:0xf bank_mask:0xf bound_ctrl:1
	s_nop 0
	s_nop 0
	v_add_f32_dpp v16, v16, v16 row_ror:1 row_mask:0xf bank_mask:0xf bound_ctrl:1
	v_pk_fma_f32 v[20:21], v[212:213], v[16:17], v[20:21] op_sel_hi:[1,0,1] neg_lo:[1,0,0] neg_hi:[1,0,0]
	v_pk_fma_f32 v[22:23], v[214:215], v[16:17], v[22:23] op_sel_hi:[1,0,1] neg_lo:[1,0,0] neg_hi:[1,0,0]
	v_pk_fma_f32 v[56:57], v[204:205], v[56:57], v[20:21]
	v_pk_fma_f32 v[58:59], v[206:207], v[58:59], v[22:23]
	v_pk_mul_f32 v[250:251], v[228:229], v[56:57]
	v_pk_mul_f32 v[20:21], v[220:221], v[238:239] op_sel:[0,1]
	v_pk_fma_f32 v[250:251], v[230:231], v[58:59], v[250:251]
	v_pk_mul_f32 v[22:23], v[222:223], v[238:239] op_sel:[0,1]
	v_add_f32_e32 v16, v250, v251
	v_pk_mul_f32 v[252:253], v[196:197], v[56:57]
	s_nop 0
	v_add_f32_dpp v16, v16, v16 row_ror:8 row_mask:0xf bank_mask:0xf bound_ctrl:1
	v_pk_fma_f32 v[252:253], v[198:199], v[58:59], v[252:253]
	s_nop 0
	v_add_f32_dpp v16, v16, v16 row_ror:4 row_mask:0xf bank_mask:0xf bound_ctrl:1
	v_add_f32_e32 v62, v252, v253
	s_nop 0
	v_add_f32_dpp v16, v16, v16 row_ror:2 row_mask:0xf bank_mask:0xf bound_ctrl:1
	s_nop 0
	s_nop 0
	v_add_f32_dpp v16, v16, v16 row_ror:1 row_mask:0xf bank_mask:0xf bound_ctrl:1
	v_pk_fma_f32 v[20:21], v[232:233], v[16:17], v[20:21] op_sel_hi:[1,0,1] neg_lo:[1,0,0] neg_hi:[1,0,0]
	v_pk_fma_f32 v[22:23], v[234:235], v[16:17], v[22:23] op_sel_hi:[1,0,1] neg_lo:[1,0,0] neg_hi:[1,0,0]
	v_pk_fma_f32 v[56:57], v[224:225], v[56:57], v[20:21]
	v_pk_fma_f32 v[58:59], v[226:227], v[58:59], v[22:23]
	v_pk_mul_f32 v[252:253], v[216:217], v[56:57]
	s_nop 0
	v_pk_fma_f32 v[252:253], v[218:219], v[58:59], v[252:253]
	s_nop 0
	v_add_f32_e32 v63, v252, v253
	v_add_f32_dpp v240, v240, v240 row_ror:8 row_mask:0xf bank_mask:0x3
	v_add_f32_dpp v241, v241, v241 row_ror:8 row_mask:0xf bank_mask:0x3
	v_add_f32_dpp v242, v242, v242 row_ror:8 row_mask:0xf bank_mask:0x3
	v_add_f32_dpp v243, v243, v243 row_ror:8 row_mask:0xf bank_mask:0x3
	v_add_f32_dpp v244, v244, v244 row_ror:8 row_mask:0xf bank_mask:0x3
	v_add_f32_dpp v245, v245, v245 row_ror:8 row_mask:0xf bank_mask:0x3
	v_add_f32_dpp v246, v246, v246 row_ror:8 row_mask:0xf bank_mask:0x3
	v_add_f32_dpp v247, v247, v247 row_ror:8 row_mask:0xf bank_mask:0x3
	v_add_f32_dpp v240, v248, v248 row_ror:8 row_mask:0xf bank_mask:0xc
	v_add_f32_dpp v241, v249, v249 row_ror:8 row_mask:0xf bank_mask:0xc
	v_add_f32_dpp v242, v150, v150 row_ror:8 row_mask:0xf bank_mask:0xc
	v_add_f32_dpp v243, v151, v151 row_ror:8 row_mask:0xf bank_mask:0xc
	v_add_f32_dpp v244, v26, v26 row_ror:8 row_mask:0xf bank_mask:0xc
	v_add_f32_dpp v245, v27, v27 row_ror:8 row_mask:0xf bank_mask:0xc
	v_add_f32_dpp v246, v62, v62 row_ror:8 row_mask:0xf bank_mask:0xc
	v_add_f32_dpp v247, v63, v63 row_ror:8 row_mask:0xf bank_mask:0xc
	v_add_f32_dpp v240, v240, v240 row_ror:12 row_mask:0xf bank_mask:0x5
	v_add_f32_dpp v241, v241, v241 row_ror:12 row_mask:0xf bank_mask:0x5
	v_add_f32_dpp v242, v242, v242 row_ror:12 row_mask:0xf bank_mask:0x5
	v_add_f32_dpp v243, v243, v243 row_ror:12 row_mask:0xf bank_mask:0x5
	v_add_f32_dpp v240, v244, v244 row_ror:4 row_mask:0xf bank_mask:0xa
	v_add_f32_dpp v241, v245, v245 row_ror:4 row_mask:0xf bank_mask:0xa
	v_add_f32_dpp v242, v246, v246 row_ror:4 row_mask:0xf bank_mask:0xa
	v_add_f32_dpp v243, v247, v247 row_ror:4 row_mask:0xf bank_mask:0xa
	v_lshl_add_u32 v25, v34, 4, v18
	v_add_f32_dpp v240, v240, v240 quad_perm:[1,0,3,2] row_mask:0xf bank_mask:0xf
	v_add_f32_dpp v241, v241, v241 quad_perm:[1,0,3,2] row_mask:0xf bank_mask:0xf
	v_add_f32_dpp v242, v242, v242 quad_perm:[1,0,3,2] row_mask:0xf bank_mask:0xf
	v_add_f32_dpp v243, v243, v243 quad_perm:[1,0,3,2] row_mask:0xf bank_mask:0xf
	v_add_f32_dpp v240, v240, v240 quad_perm:[2,3,0,1] row_mask:0xf bank_mask:0xf
	v_add_f32_dpp v241, v241, v241 quad_perm:[2,3,0,1] row_mask:0xf bank_mask:0xf
	v_add_f32_dpp v242, v242, v242 quad_perm:[2,3,0,1] row_mask:0xf bank_mask:0xf
	v_add_f32_dpp v243, v243, v243 quad_perm:[2,3,0,1] row_mask:0xf bank_mask:0xf
	v_cmp_eq_u32_e32 vcc, 1, v19
	s_nop 1
	v_cndmask_b32_e32 v24, v240, v241, vcc
	v_cmp_eq_u32_e32 vcc, 2, v19
	s_nop 1
	v_cndmask_b32_e32 v24, v24, v242, vcc
	v_cmp_eq_u32_e32 vcc, 3, v19
	s_nop 1
	v_cndmask_b32_e32 v24, v24, v243, vcc
	ds_write_b32 v25, v24 offset:21504
	s_cmpk_eq_i32 s9, 0x7e0
	s_cbranch_scc1 .LBB0_451
	s_mov_b32 s13, s12
	s_mov_b32 s11, s9
	s_branch .LBB0_423

.LBB0_1416:
	s_or_b64 exec, exec, s[0:1]
	v_lshl_add_u32 v17, v36, 2, s25
	v_add3_u32 v18, s25, v93, v94
	v_add_u32_e32 v25, 0x5000, v18
	v_bfe_u32 v19, v36, 2, 2
	ds_read2_b32 v[236:237], v25 offset0:0 offset1:16
	ds_read_b128 v[164:167], v17 offset:12288
	ds_read_b128 v[156:159], v17 offset:4096
	ds_read_b128 v[168:171], v17 offset:16384
	ds_read_b128 v[160:163], v17 offset:8192
	ds_read_b128 v[152:155], v17
	ds_read_b128 v[188:191], v17 offset:12544
	ds_read_b128 v[180:183], v17 offset:4352
	ds_read_b128 v[192:195], v17 offset:16640
	ds_read_b128 v[184:187], v17 offset:8448
	ds_read_b128 v[176:179], v17 offset:256
	s_waitcnt lgkmcnt(0)
	v_pk_mul_f32 v[250:251], v[164:165], v[58:59]
	v_pk_mul_f32 v[20:21], v[156:157], v[236:237] op_sel_hi:[1,0]
	v_pk_fma_f32 v[250:251], v[166:167], v[60:61], v[250:251]
	v_pk_mul_f32 v[22:23], v[158:159], v[236:237] op_sel_hi:[1,0]
	v_add_f32_e32 v16, v250, v251
	ds_read2_b32 v[238:239], v25 offset0:32 offset1:48
	ds_read_b128 v[208:211], v17 offset:12800
	v_add_f32_dpp v16, v16, v16 row_ror:8 row_mask:0xf bank_mask:0xf bound_ctrl:1
	ds_read_b128 v[200:203], v17 offset:4608
	ds_read_b128 v[212:215], v17 offset:16896
	v_add_f32_dpp v16, v16, v16 row_ror:4 row_mask:0xf bank_mask:0xf bound_ctrl:1
	ds_read_b128 v[204:207], v17 offset:8704
	ds_read_b128 v[196:199], v17 offset:512
	v_add_f32_dpp v16, v16, v16 row_ror:2 row_mask:0xf bank_mask:0xf bound_ctrl:1
	ds_read_b128 v[228:231], v17 offset:13056
	ds_read_b128 v[220:223], v17 offset:4864
	v_add_f32_dpp v16, v16, v16 row_ror:1 row_mask:0xf bank_mask:0xf bound_ctrl:1
	v_pk_fma_f32 v[20:21], v[168:169], v[16:17], v[20:21] op_sel_hi:[1,0,1] neg_lo:[1,0,0] neg_hi:[1,0,0]
	v_pk_fma_f32 v[22:23], v[170:171], v[16:17], v[22:23] op_sel_hi:[1,0,1] neg_lo:[1,0,0] neg_hi:[1,0,0]
	v_pk_fma_f32 v[58:59], v[160:161], v[58:59], v[20:21]
	v_pk_fma_f32 v[60:61], v[162:163], v[60:61], v[22:23]
	v_pk_mul_f32 v[250:251], v[188:189], v[58:59]
	v_pk_mul_f32 v[20:21], v[180:181], v[236:237] op_sel:[0,1]
	v_pk_fma_f32 v[250:251], v[190:191], v[60:61], v[250:251]
	v_pk_mul_f32 v[22:23], v[182:183], v[236:237] op_sel:[0,1]
	v_add_f32_e32 v16, v250, v251
	v_pk_mul_f32 v[252:253], v[152:153], v[58:59]
	ds_read_b128 v[232:235], v17 offset:17152
	v_add_f32_dpp v16, v16, v16 row_ror:8 row_mask:0xf bank_mask:0xf bound_ctrl:1
	v_pk_fma_f32 v[252:253], v[154:155], v[60:61], v[252:253]
	ds_read_b128 v[224:227], v17 offset:8960
	v_add_f32_dpp v16, v16, v16 row_ror:4 row_mask:0xf bank_mask:0xf bound_ctrl:1
	v_add_f32_e32 v240, v252, v253
	ds_read_b128 v[216:219], v17 offset:768
	v_add_f32_dpp v16, v16, v16 row_ror:2 row_mask:0xf bank_mask:0xf bound_ctrl:1
	s_nop 0
	s_nop 0
	v_add_f32_dpp v16, v16, v16 row_ror:1 row_mask:0xf bank_mask:0xf bound_ctrl:1
	v_pk_fma_f32 v[20:21], v[192:193], v[16:17], v[20:21] op_sel_hi:[1,0,1] neg_lo:[1,0,0] neg_hi:[1,0,0]
	v_pk_fma_f32 v[22:23], v[194:195], v[16:17], v[22:23] op_sel_hi:[1,0,1] neg_lo:[1,0,0] neg_hi:[1,0,0]
	v_pk_fma_f32 v[58:59], v[184:185], v[58:59], v[20:21]
	v_pk_fma_f32 v[60:61], v[186:187], v[60:61], v[22:23]
	s_waitcnt lgkmcnt(0)
	v_pk_mul_f32 v[250:251], v[208:209], v[58:59]
	v_pk_mul_f32 v[20:21], v[200:201], v[238:239] op_sel_hi:[1,0]
	v_pk_fma_f32 v[250:251], v[210:211], v[60:61], v[250:251]
	v_pk_mul_f32 v[22:23], v[202:203], v[238:239] op_sel_hi:[1,0]
	v_add_f32_e32 v16, v250, v251
	v_pk_mul_f32 v[252:253], v[176:177], v[58:59]
	s_nop 0
	v_add_f32_dpp v16, v16, v16 row_ror:8 row_mask:0xf bank_mask:0xf bound_ctrl:1
	v_pk_fma_f32 v[252:253], v[178:179], v[60:61], v[252:253]
	ds_read2_b32 v[236:237], v25 offset0:64 offset1:80
	v_add_f32_dpp v16, v16, v16 row_ror:4 row_mask:0xf bank_mask:0xf bound_ctrl:1
	v_add_f32_e32 v241, v252, v253
	ds_read_b128 v[164:167], v17 offset:13312
	v_add_f32_dpp v16, v16, v16 row_ror:2 row_mask:0xf bank_mask:0xf bound_ctrl:1
	ds_read_b128 v[156:159], v17 offset:5120
	ds_read_b128 v[168:171], v17 offset:17408
	v_add_f32_dpp v16, v16, v16 row_ror:1 row_mask:0xf bank_mask:0xf bound_ctrl:1
	v_pk_fma_f32 v[20:21], v[212:213], v[16:17], v[20:21] op_sel_hi:[1,0,1] neg_lo:[1,0,0] neg_hi:[1,0,0]
	v_pk_fma_f32 v[22:23], v[214:215], v[16:17], v[22:23] op_sel_hi:[1,0,1] neg_lo:[1,0,0] neg_hi:[1,0,0]
	v_pk_fma_f32 v[58:59], v[204:205], v[58:59], v[20:21]
	v_pk_fma_f32 v[60:61], v[206:207], v[60:61], v[22:23]
	v_pk_mul_f32 v[250:251], v[228:229], v[58:59]
	v_pk_mul_f32 v[20:21], v[220:221], v[238:239] op_sel:[0,1]
	v_pk_fma_f32 v[250:251], v[230:231], v[60:61], v[250:251]
	v_pk_mul_f32 v[22:23], v[222:223], v[238:239] op_sel:[0,1]
	v_add_f32_e32 v16, v250, v251
	v_pk_mul_f32 v[252:253], v[196:197], v[58:59]
	ds_read_b128 v[160:163], v17 offset:9216
	v_add_f32_dpp v16, v16, v16 row_ror:8 row_mask:0xf bank_mask:0xf bound_ctrl:1
	v_pk_fma_f32 v[252:253], v[198:199], v[60:61], v[252:253]
	ds_read_b128 v[152:155], v17 offset:1024
	v_add_f32_dpp v16, v16, v16 row_ror:4 row_mask:0xf bank_mask:0xf bound_ctrl:1
	v_add_f32_e32 v242, v252, v253
	ds_read_b128 v[188:191], v17 offset:13568
	v_add_f32_dpp v16, v16, v16 row_ror:2 row_mask:0xf bank_mask:0xf bound_ctrl:1
	ds_read_b128 v[180:183], v17 offset:5376
	ds_read_b128 v[192:195], v17 offset:17664
	v_add_f32_dpp v16, v16, v16 row_ror:1 row_mask:0xf bank_mask:0xf bound_ctrl:1
	v_pk_fma_f32 v[20:21], v[232:233], v[16:17], v[20:21] op_sel_hi:[1,0,1] neg_lo:[1,0,0] neg_hi:[1,0,0]
	v_pk_fma_f32 v[22:23], v[234:235], v[16:17], v[22:23] op_sel_hi:[1,0,1] neg_lo:[1,0,0] neg_hi:[1,0,0]
	v_pk_fma_f32 v[58:59], v[224:225], v[58:59], v[20:21]
	v_pk_fma_f32 v[60:61], v[226:227], v[60:61], v[22:23]
	ds_read_b128 v[184:187], v17 offset:9472
	ds_read_b128 v[176:179], v17 offset:1280
	s_waitcnt lgkmcnt(0)
	v_pk_mul_f32 v[250:251], v[164:165], v[58:59]
	v_pk_mul_f32 v[20:21], v[156:157], v[236:237] op_sel_hi:[1,0]
	v_pk_fma_f32 v[250:251], v[166:167], v[60:61], v[250:251]
	v_pk_mul_f32 v[22:23], v[158:159], v[236:237] op_sel_hi:[1,0]
	v_add_f32_e32 v16, v250, v251
	v_pk_mul_f32 v[252:253], v[216:217], v[58:59]
	s_nop 0
	v_add_f32_dpp v16, v16, v16 row_ror:8 row_mask:0xf bank_mask:0xf bound_ctrl:1
	v_pk_fma_f32 v[252:253], v[218:219], v[60:61], v[252:253]
	ds_read2_b32 v[238:239], v25 offset0:96 offset1:112
	v_add_f32_dpp v16, v16, v16 row_ror:4 row_mask:0xf bank_mask:0xf bound_ctrl:1
	v_add_f32_e32 v243, v252, v253
	ds_read_b128 v[208:211], v17 offset:13824
	v_add_f32_dpp v16, v16, v16 row_ror:2 row_mask:0xf bank_mask:0xf bound_ctrl:1
	ds_read_b128 v[200:203], v17 offset:5632
	ds_read_b128 v[212:215], v17 offset:17920
	v_add_f32_dpp v16, v16, v16 row_ror:1 row_mask:0xf bank_mask:0xf bound_ctrl:1
	v_pk_fma_f32 v[20:21], v[168:169], v[16:17], v[20:21] op_sel_hi:[1,0,1] neg_lo:[1,0,0] neg_hi:[1,0,0]
	v_pk_fma_f32 v[22:23], v[170:171], v[16:17], v[22:23] op_sel_hi:[1,0,1] neg_lo:[1,0,0] neg_hi:[1,0,0]
	v_pk_fma_f32 v[58:59], v[160:161], v[58:59], v[20:21]
	v_pk_fma_f32 v[60:61], v[162:163], v[60:61], v[22:23]
	v_pk_mul_f32 v[250:251], v[188:189], v[58:59]
	v_pk_mul_f32 v[20:21], v[180:181], v[236:237] op_sel:[0,1]
	v_pk_fma_f32 v[250:251], v[190:191], v[60:61], v[250:251]
	v_pk_mul_f32 v[22:23], v[182:183], v[236:237] op_sel:[0,1]
	v_add_f32_e32 v16, v250, v251
	v_pk_mul_f32 v[252:253], v[152:153], v[58:59]
	ds_read_b128 v[204:207], v17 offset:9728
	v_add_f32_dpp v16, v16, v16 row_ror:8 row_mask:0xf bank_mask:0xf bound_ctrl:1
	v_pk_fma_f32 v[252:253], v[154:155], v[60:61], v[252:253]
	ds_read_b128 v[196:199], v17 offset:1536
	v_add_f32_dpp v16, v16, v16 row_ror:4 row_mask:0xf bank_mask:0xf bound_ctrl:1
	v_add_f32_e32 v244, v252, v253
	ds_read_b128 v[228:231], v17 offset:14080
	v_add_f32_dpp v16, v16, v16 row_ror:2 row_mask:0xf bank_mask:0xf bound_ctrl:1
	ds_read_b128 v[220:223], v17 offset:5888
	ds_read_b128 v[232:235], v17 offset:18176
	v_add_f32_dpp v16, v16, v16 row_ror:1 row_mask:0xf bank_mask:0xf bound_ctrl:1
	v_pk_fma_f32 v[20:21], v[192:193], v[16:17], v[20:21] op_sel_hi:[1,0,1] neg_lo:[1,0,0] neg_hi:[1,0,0]
	v_pk_fma_f32 v[22:23], v[194:195], v[16:17], v[22:23] op_sel_hi:[1,0,1] neg_lo:[1,0,0] neg_hi:[1,0,0]
	v_pk_fma_f32 v[58:59], v[184:185], v[58:59], v[20:21]
	v_pk_fma_f32 v[60:61], v[186:187], v[60:61], v[22:23]
	ds_read_b128 v[224:227], v17 offset:9984
	ds_read_b128 v[216:219], v17 offset:1792
	s_waitcnt lgkmcnt(0)
	v_pk_mul_f32 v[250:251], v[208:209], v[58:59]
	v_pk_mul_f32 v[20:21], v[200:201], v[238:239] op_sel_hi:[1,0]
	v_pk_fma_f32 v[250:251], v[210:211], v[60:61], v[250:251]
	v_pk_mul_f32 v[22:23], v[202:203], v[238:239] op_sel_hi:[1,0]
	v_add_f32_e32 v16, v250, v251
	v_pk_mul_f32 v[252:253], v[176:177], v[58:59]
	s_nop 0
	v_add_f32_dpp v16, v16, v16 row_ror:8 row_mask:0xf bank_mask:0xf bound_ctrl:1
	v_pk_fma_f32 v[252:253], v[178:179], v[60:61], v[252:253]
	ds_read2_b32 v[236:237], v25 offset0:128 offset1:144
	v_add_f32_dpp v16, v16, v16 row_ror:4 row_mask:0xf bank_mask:0xf bound_ctrl:1
	v_add_f32_e32 v245, v252, v253
	ds_read_b128 v[164:167], v17 offset:14336
	v_add_f32_dpp v16, v16, v16 row_ror:2 row_mask:0xf bank_mask:0xf bound_ctrl:1
	ds_read_b128 v[156:159], v17 offset:6144
	ds_read_b128 v[168:171], v17 offset:18432
	v_add_f32_dpp v16, v16, v16 row_ror:1 row_mask:0xf bank_mask:0xf bound_ctrl:1
	v_pk_fma_f32 v[20:21], v[212:213], v[16:17], v[20:21] op_sel_hi:[1,0,1] neg_lo:[1,0,0] neg_hi:[1,0,0]
	v_pk_fma_f32 v[22:23], v[214:215], v[16:17], v[22:23] op_sel_hi:[1,0,1] neg_lo:[1,0,0] neg_hi:[1,0,0]
	v_pk_fma_f32 v[58:59], v[204:205], v[58:59], v[20:21]
	v_pk_fma_f32 v[60:61], v[206:207], v[60:61], v[22:23]
	v_pk_mul_f32 v[250:251], v[228:229], v[58:59]
	v_pk_mul_f32 v[20:21], v[220:221], v[238:239] op_sel:[0,1]
	v_pk_fma_f32 v[250:251], v[230:231], v[60:61], v[250:251]
	v_pk_mul_f32 v[22:23], v[222:223], v[238:239] op_sel:[0,1]
	v_add_f32_e32 v16, v250, v251
	v_pk_mul_f32 v[252:253], v[196:197], v[58:59]
	ds_read_b128 v[160:163], v17 offset:10240
	v_add_f32_dpp v16, v16, v16 row_ror:8 row_mask:0xf bank_mask:0xf bound_ctrl:1
	v_pk_fma_f32 v[252:253], v[198:199], v[60:61], v[252:253]
	ds_read_b128 v[152:155], v17 offset:2048
	v_add_f32_dpp v16, v16, v16 row_ror:4 row_mask:0xf bank_mask:0xf bound_ctrl:1
	v_add_f32_e32 v246, v252, v253
	ds_read_b128 v[188:191], v17 offset:14592
	v_add_f32_dpp v16, v16, v16 row_ror:2 row_mask:0xf bank_mask:0xf bound_ctrl:1
	ds_read_b128 v[180:183], v17 offset:6400
	ds_read_b128 v[192:195], v17 offset:18688
	v_add_f32_dpp v16, v16, v16 row_ror:1 row_mask:0xf bank_mask:0xf bound_ctrl:1
	v_pk_fma_f32 v[20:21], v[232:233], v[16:17], v[20:21] op_sel_hi:[1,0,1] neg_lo:[1,0,0] neg_hi:[1,0,0]
	v_pk_fma_f32 v[22:23], v[234:235], v[16:17], v[22:23] op_sel_hi:[1,0,1] neg_lo:[1,0,0] neg_hi:[1,0,0]
	v_pk_fma_f32 v[58:59], v[224:225], v[58:59], v[20:21]
	v_pk_fma_f32 v[60:61], v[226:227], v[60:61], v[22:23]
	ds_read_b128 v[184:187], v17 offset:10496
	ds_read_b128 v[176:179], v17 offset:2304
	s_waitcnt lgkmcnt(0)
	v_pk_mul_f32 v[250:251], v[164:165], v[58:59]
	v_pk_mul_f32 v[20:21], v[156:157], v[236:237] op_sel_hi:[1,0]
	v_pk_fma_f32 v[250:251], v[166:167], v[60:61], v[250:251]
	v_pk_mul_f32 v[22:23], v[158:159], v[236:237] op_sel_hi:[1,0]
	v_add_f32_e32 v16, v250, v251
	v_pk_mul_f32 v[252:253], v[216:217], v[58:59]
	s_nop 0
	v_add_f32_dpp v16, v16, v16 row_ror:8 row_mask:0xf bank_mask:0xf bound_ctrl:1
	v_pk_fma_f32 v[252:253], v[218:219], v[60:61], v[252:253]
	ds_read2_b32 v[238:239], v25 offset0:160 offset1:176
	v_add_f32_dpp v16, v16, v16 row_ror:4 row_mask:0xf bank_mask:0xf bound_ctrl:1
	v_add_f32_e32 v247, v252, v253
	ds_read_b128 v[208:211], v17 offset:14848
	v_add_f32_dpp v16, v16, v16 row_ror:2 row_mask:0xf bank_mask:0xf bound_ctrl:1
	ds_read_b128 v[200:203], v17 offset:6656
	ds_read_b128 v[212:215], v17 offset:18944
	v_add_f32_dpp v16, v16, v16 row_ror:1 row_mask:0xf bank_mask:0xf bound_ctrl:1
	v_pk_fma_f32 v[20:21], v[168:169], v[16:17], v[20:21] op_sel_hi:[1,0,1] neg_lo:[1,0,0] neg_hi:[1,0,0]
	v_pk_fma_f32 v[22:23], v[170:171], v[16:17], v[22:23] op_sel_hi:[1,0,1] neg_lo:[1,0,0] neg_hi:[1,0,0]
	v_pk_fma_f32 v[58:59], v[160:161], v[58:59], v[20:21]
	v_pk_fma_f32 v[60:61], v[162:163], v[60:61], v[22:23]
	v_pk_mul_f32 v[250:251], v[188:189], v[58:59]
	v_pk_mul_f32 v[20:21], v[180:181], v[236:237] op_sel:[0,1]
	v_pk_fma_f32 v[250:251], v[190:191], v[60:61], v[250:251]
	v_pk_mul_f32 v[22:23], v[182:183], v[236:237] op_sel:[0,1]
	v_add_f32_e32 v16, v250, v251
	v_pk_mul_f32 v[252:253], v[152:153], v[58:59]
	ds_read_b128 v[204:207], v17 offset:10752
	v_add_f32_dpp v16, v16, v16 row_ror:8 row_mask:0xf bank_mask:0xf bound_ctrl:1
	v_pk_fma_f32 v[252:253], v[154:155], v[60:61], v[252:253]
	ds_read_b128 v[196:199], v17 offset:2560
	v_add_f32_dpp v16, v16, v16 row_ror:4 row_mask:0xf bank_mask:0xf bound_ctrl:1
	v_add_f32_e32 v248, v252, v253
	ds_read_b128 v[228:231], v17 offset:15104
	v_add_f32_dpp v16, v16, v16 row_ror:2 row_mask:0xf bank_mask:0xf bound_ctrl:1
	ds_read_b128 v[220:223], v17 offset:6912
	ds_read_b128 v[232:235], v17 offset:19200
	v_add_f32_dpp v16, v16, v16 row_ror:1 row_mask:0xf bank_mask:0xf bound_ctrl:1
	v_pk_fma_f32 v[20:21], v[192:193], v[16:17], v[20:21] op_sel_hi:[1,0,1] neg_lo:[1,0,0] neg_hi:[1,0,0]
	v_pk_fma_f32 v[22:23], v[194:195], v[16:17], v[22:23] op_sel_hi:[1,0,1] neg_lo:[1,0,0] neg_hi:[1,0,0]
	v_pk_fma_f32 v[58:59], v[184:185], v[58:59], v[20:21]
	v_pk_fma_f32 v[60:61], v[186:187], v[60:61], v[22:23]
	ds_read_b128 v[224:227], v17 offset:11008
	ds_read_b128 v[216:219], v17 offset:2816
	s_waitcnt lgkmcnt(0)
	v_pk_mul_f32 v[250:251], v[208:209], v[58:59]
	v_pk_mul_f32 v[20:21], v[200:201], v[238:239] op_sel_hi:[1,0]
	v_pk_fma_f32 v[250:251], v[210:211], v[60:61], v[250:251]
	v_pk_mul_f32 v[22:23], v[202:203], v[238:239] op_sel_hi:[1,0]
	v_add_f32_e32 v16, v250, v251
	v_pk_mul_f32 v[252:253], v[176:177], v[58:59]
	s_nop 0
	v_add_f32_dpp v16, v16, v16 row_ror:8 row_mask:0xf bank_mask:0xf bound_ctrl:1
	v_pk_fma_f32 v[252:253], v[178:179], v[60:61], v[252:253]
	ds_read2_b32 v[236:237], v25 offset0:192 offset1:208
	v_add_f32_dpp v16, v16, v16 row_ror:4 row_mask:0xf bank_mask:0xf bound_ctrl:1
	v_add_f32_e32 v249, v252, v253
	ds_read_b128 v[164:167], v17 offset:15360
	v_add_f32_dpp v16, v16, v16 row_ror:2 row_mask:0xf bank_mask:0xf bound_ctrl:1
	ds_read_b128 v[156:159], v17 offset:7168
	ds_read_b128 v[168:171], v17 offset:19456
	v_add_f32_dpp v16, v16, v16 row_ror:1 row_mask:0xf bank_mask:0xf bound_ctrl:1
	v_pk_fma_f32 v[20:21], v[212:213], v[16:17], v[20:21] op_sel_hi:[1,0,1] neg_lo:[1,0,0] neg_hi:[1,0,0]
	v_pk_fma_f32 v[22:23], v[214:215], v[16:17], v[22:23] op_sel_hi:[1,0,1] neg_lo:[1,0,0] neg_hi:[1,0,0]
	v_pk_fma_f32 v[58:59], v[204:205], v[58:59], v[20:21]
	v_pk_fma_f32 v[60:61], v[206:207], v[60:61], v[22:23]
	v_pk_mul_f32 v[250:251], v[228:229], v[58:59]
	v_pk_mul_f32 v[20:21], v[220:221], v[238:239] op_sel:[0,1]
	v_pk_fma_f32 v[250:251], v[230:231], v[60:61], v[250:251]
	v_pk_mul_f32 v[22:23], v[222:223], v[238:239] op_sel:[0,1]
	v_add_f32_e32 v16, v250, v251
	v_pk_mul_f32 v[252:253], v[196:197], v[58:59]
	ds_read_b128 v[160:163], v17 offset:11264
	v_add_f32_dpp v16, v16, v16 row_ror:8 row_mask:0xf bank_mask:0xf bound_ctrl:1
	v_pk_fma_f32 v[252:253], v[198:199], v[60:61], v[252:253]
	ds_read_b128 v[152:155], v17 offset:3072
	v_add_f32_dpp v16, v16, v16 row_ror:4 row_mask:0xf bank_mask:0xf bound_ctrl:1
	v_add_f32_e32 v150, v252, v253
	ds_read_b128 v[188:191], v17 offset:15616
	v_add_f32_dpp v16, v16, v16 row_ror:2 row_mask:0xf bank_mask:0xf bound_ctrl:1
	ds_read_b128 v[180:183], v17 offset:7424
	ds_read_b128 v[192:195], v17 offset:19712
	v_add_f32_dpp v16, v16, v16 row_ror:1 row_mask:0xf bank_mask:0xf bound_ctrl:1
	v_pk_fma_f32 v[20:21], v[232:233], v[16:17], v[20:21] op_sel_hi:[1,0,1] neg_lo:[1,0,0] neg_hi:[1,0,0]
	v_pk_fma_f32 v[22:23], v[234:235], v[16:17], v[22:23] op_sel_hi:[1,0,1] neg_lo:[1,0,0] neg_hi:[1,0,0]
	v_pk_fma_f32 v[58:59], v[224:225], v[58:59], v[20:21]
	v_pk_fma_f32 v[60:61], v[226:227], v[60:61], v[22:23]
	ds_read_b128 v[184:187], v17 offset:11520
	ds_read_b128 v[176:179], v17 offset:3328
	s_waitcnt lgkmcnt(0)
	v_pk_mul_f32 v[250:251], v[164:165], v[58:59]
	v_pk_mul_f32 v[20:21], v[156:157], v[236:237] op_sel_hi:[1,0]
	v_pk_fma_f32 v[250:251], v[166:167], v[60:61], v[250:251]
	v_pk_mul_f32 v[22:23], v[158:159], v[236:237] op_sel_hi:[1,0]
	v_add_f32_e32 v16, v250, v251
	v_pk_mul_f32 v[252:253], v[216:217], v[58:59]
	s_nop 0
	v_add_f32_dpp v16, v16, v16 row_ror:8 row_mask:0xf bank_mask:0xf bound_ctrl:1
	v_pk_fma_f32 v[252:253], v[218:219], v[60:61], v[252:253]
	ds_read2_b32 v[238:239], v25 offset0:224 offset1:240
	v_add_f32_dpp v16, v16, v16 row_ror:4 row_mask:0xf bank_mask:0xf bound_ctrl:1
	v_add_f32_e32 v151, v252, v253
	ds_read_b128 v[208:211], v17 offset:15872
	v_add_f32_dpp v16, v16, v16 row_ror:2 row_mask:0xf bank_mask:0xf bound_ctrl:1
	ds_read_b128 v[200:203], v17 offset:7680
	ds_read_b128 v[212:215], v17 offset:19968
	v_add_f32_dpp v16, v16, v16 row_ror:1 row_mask:0xf bank_mask:0xf bound_ctrl:1
	v_pk_fma_f32 v[20:21], v[168:169], v[16:17], v[20:21] op_sel_hi:[1,0,1] neg_lo:[1,0,0] neg_hi:[1,0,0]
	v_pk_fma_f32 v[22:23], v[170:171], v[16:17], v[22:23] op_sel_hi:[1,0,1] neg_lo:[1,0,0] neg_hi:[1,0,0]
	v_pk_fma_f32 v[58:59], v[160:161], v[58:59], v[20:21]
	v_pk_fma_f32 v[60:61], v[162:163], v[60:61], v[22:23]
	v_pk_mul_f32 v[250:251], v[188:189], v[58:59]
	v_pk_mul_f32 v[20:21], v[180:181], v[236:237] op_sel:[0,1]
	v_pk_fma_f32 v[250:251], v[190:191], v[60:61], v[250:251]
	v_pk_mul_f32 v[22:23], v[182:183], v[236:237] op_sel:[0,1]
	v_add_f32_e32 v16, v250, v251
	v_pk_mul_f32 v[252:253], v[152:153], v[58:59]
	ds_read_b128 v[204:207], v17 offset:11776
	v_add_f32_dpp v16, v16, v16 row_ror:8 row_mask:0xf bank_mask:0xf bound_ctrl:1
	v_pk_fma_f32 v[252:253], v[154:155], v[60:61], v[252:253]
	ds_read_b128 v[196:199], v17 offset:3584
	v_add_f32_dpp v16, v16, v16 row_ror:4 row_mask:0xf bank_mask:0xf bound_ctrl:1
	v_add_f32_e32 v26, v252, v253
	ds_read_b128 v[228:231], v17 offset:16128
	v_add_f32_dpp v16, v16, v16 row_ror:2 row_mask:0xf bank_mask:0xf bound_ctrl:1
	ds_read_b128 v[220:223], v17 offset:7936
	ds_read_b128 v[232:235], v17 offset:20224
	v_add_f32_dpp v16, v16, v16 row_ror:1 row_mask:0xf bank_mask:0xf bound_ctrl:1
	v_pk_fma_f32 v[20:21], v[192:193], v[16:17], v[20:21] op_sel_hi:[1,0,1] neg_lo:[1,0,0] neg_hi:[1,0,0]
	v_pk_fma_f32 v[22:23], v[194:195], v[16:17], v[22:23] op_sel_hi:[1,0,1] neg_lo:[1,0,0] neg_hi:[1,0,0]
	v_pk_fma_f32 v[58:59], v[184:185], v[58:59], v[20:21]
	v_pk_fma_f32 v[60:61], v[186:187], v[60:61], v[22:23]
	ds_read_b128 v[224:227], v17 offset:12032
	ds_read_b128 v[216:219], v17 offset:3840
	s_waitcnt lgkmcnt(0)
	v_pk_mul_f32 v[250:251], v[208:209], v[58:59]
	v_pk_mul_f32 v[20:21], v[200:201], v[238:239] op_sel_hi:[1,0]
	v_pk_fma_f32 v[250:251], v[210:211], v[60:61], v[250:251]
	v_pk_mul_f32 v[22:23], v[202:203], v[238:239] op_sel_hi:[1,0]
	v_add_f32_e32 v16, v250, v251
	v_pk_mul_f32 v[252:253], v[176:177], v[58:59]
	s_nop 0
	v_add_f32_dpp v16, v16, v16 row_ror:8 row_mask:0xf bank_mask:0xf bound_ctrl:1
	v_pk_fma_f32 v[252:253], v[178:179], v[60:61], v[252:253]
	s_nop 0
	v_add_f32_dpp v16, v16, v16 row_ror:4 row_mask:0xf bank_mask:0xf bound_ctrl:1
	v_add_f32_e32 v27, v252, v253
	s_nop 0
	v_add_f32_dpp v16, v16, v16 row_ror:2 row_mask:0xf bank_mask:0xf bound_ctrl:1
	s_nop 0
	s_nop 0
	v_add_f32_dpp v16, v16, v16 row_ror:1 row_mask:0xf bank_mask:0xf bound_ctrl:1
	v_pk_fma_f32 v[20:21], v[212:213], v[16:17], v[20:21] op_sel_hi:[1,0,1] neg_lo:[1,0,0] neg_hi:[1,0,0]
	v_pk_fma_f32 v[22:23], v[214:215], v[16:17], v[22:23] op_sel_hi:[1,0,1] neg_lo:[1,0,0] neg_hi:[1,0,0]
	v_pk_fma_f32 v[58:59], v[204:205], v[58:59], v[20:21]
	v_pk_fma_f32 v[60:61], v[206:207], v[60:61], v[22:23]
	v_pk_mul_f32 v[250:251], v[228:229], v[58:59]
	v_pk_mul_f32 v[20:21], v[220:221], v[238:239] op_sel:[0,1]
	v_pk_fma_f32 v[250:251], v[230:231], v[60:61], v[250:251]
	v_pk_mul_f32 v[22:23], v[222:223], v[238:239] op_sel:[0,1]
	v_add_f32_e32 v16, v250, v251
	v_pk_mul_f32 v[252:253], v[196:197], v[58:59]
	s_nop 0
	v_add_f32_dpp v16, v16, v16 row_ror:8 row_mask:0xf bank_mask:0xf bound_ctrl:1
	v_pk_fma_f32 v[252:253], v[198:199], v[60:61], v[252:253]
	s_nop 0
	v_add_f32_dpp v16, v16, v16 row_ror:4 row_mask:0xf bank_mask:0xf bound_ctrl:1
	v_add_f32_e32 v62, v252, v253
	s_nop 0
	v_add_f32_dpp v16, v16, v16 row_ror:2 row_mask:0xf bank_mask:0xf bound_ctrl:1
	s_nop 0
	s_nop 0
	v_add_f32_dpp v16, v16, v16 row_ror:1 row_mask:0xf bank_mask:0xf bound_ctrl:1
	v_pk_fma_f32 v[20:21], v[232:233], v[16:17], v[20:21] op_sel_hi:[1,0,1] neg_lo:[1,0,0] neg_hi:[1,0,0]
	v_pk_fma_f32 v[22:23], v[234:235], v[16:17], v[22:23] op_sel_hi:[1,0,1] neg_lo:[1,0,0] neg_hi:[1,0,0]
	v_pk_fma_f32 v[58:59], v[224:225], v[58:59], v[20:21]
	v_pk_fma_f32 v[60:61], v[226:227], v[60:61], v[22:23]
	v_pk_mul_f32 v[252:253], v[216:217], v[58:59]
	s_nop 0
	v_pk_fma_f32 v[252:253], v[218:219], v[60:61], v[252:253]
	s_nop 0
	v_add_f32_e32 v63, v252, v253
	v_add_f32_dpp v240, v240, v240 row_ror:8 row_mask:0xf bank_mask:0x3
	v_add_f32_dpp v241, v241, v241 row_ror:8 row_mask:0xf bank_mask:0x3
	v_add_f32_dpp v242, v242, v242 row_ror:8 row_mask:0xf bank_mask:0x3
	v_add_f32_dpp v243, v243, v243 row_ror:8 row_mask:0xf bank_mask:0x3
	v_add_f32_dpp v244, v244, v244 row_ror:8 row_mask:0xf bank_mask:0x3
	v_add_f32_dpp v245, v245, v245 row_ror:8 row_mask:0xf bank_mask:0x3
	v_add_f32_dpp v246, v246, v246 row_ror:8 row_mask:0xf bank_mask:0x3
	v_add_f32_dpp v247, v247, v247 row_ror:8 row_mask:0xf bank_mask:0x3
	v_add_f32_dpp v240, v248, v248 row_ror:8 row_mask:0xf bank_mask:0xc
	v_add_f32_dpp v241, v249, v249 row_ror:8 row_mask:0xf bank_mask:0xc
	v_add_f32_dpp v242, v150, v150 row_ror:8 row_mask:0xf bank_mask:0xc
	v_add_f32_dpp v243, v151, v151 row_ror:8 row_mask:0xf bank_mask:0xc
	v_add_f32_dpp v244, v26, v26 row_ror:8 row_mask:0xf bank_mask:0xc
	v_add_f32_dpp v245, v27, v27 row_ror:8 row_mask:0xf bank_mask:0xc
	v_add_f32_dpp v246, v62, v62 row_ror:8 row_mask:0xf bank_mask:0xc
	v_add_f32_dpp v247, v63, v63 row_ror:8 row_mask:0xf bank_mask:0xc
	v_add_f32_dpp v240, v240, v240 row_ror:12 row_mask:0xf bank_mask:0x5
	v_add_f32_dpp v241, v241, v241 row_ror:12 row_mask:0xf bank_mask:0x5
	v_add_f32_dpp v242, v242, v242 row_ror:12 row_mask:0xf bank_mask:0x5
	v_add_f32_dpp v243, v243, v243 row_ror:12 row_mask:0xf bank_mask:0x5
	v_add_f32_dpp v240, v244, v244 row_ror:4 row_mask:0xf bank_mask:0xa
	v_add_f32_dpp v241, v245, v245 row_ror:4 row_mask:0xf bank_mask:0xa
	v_add_f32_dpp v242, v246, v246 row_ror:4 row_mask:0xf bank_mask:0xa
	v_add_f32_dpp v243, v247, v247 row_ror:4 row_mask:0xf bank_mask:0xa
	v_lshl_add_u32 v25, v36, 4, v18
	v_add_f32_dpp v240, v240, v240 quad_perm:[1,0,3,2] row_mask:0xf bank_mask:0xf
	v_add_f32_dpp v241, v241, v241 quad_perm:[1,0,3,2] row_mask:0xf bank_mask:0xf
	v_add_f32_dpp v242, v242, v242 quad_perm:[1,0,3,2] row_mask:0xf bank_mask:0xf
	v_add_f32_dpp v243, v243, v243 quad_perm:[1,0,3,2] row_mask:0xf bank_mask:0xf
	v_add_f32_dpp v240, v240, v240 quad_perm:[2,3,0,1] row_mask:0xf bank_mask:0xf
	v_add_f32_dpp v241, v241, v241 quad_perm:[2,3,0,1] row_mask:0xf bank_mask:0xf
	v_add_f32_dpp v242, v242, v242 quad_perm:[2,3,0,1] row_mask:0xf bank_mask:0xf
	v_add_f32_dpp v243, v243, v243 quad_perm:[2,3,0,1] row_mask:0xf bank_mask:0xf
	v_cmp_eq_u32_e32 vcc, 1, v19
	s_nop 1
	v_cndmask_b32_e32 v24, v240, v241, vcc
	v_cmp_eq_u32_e32 vcc, 2, v19
	s_nop 1
	v_cndmask_b32_e32 v24, v24, v242, vcc
	v_cmp_eq_u32_e32 vcc, 3, v19
	s_nop 1
	v_cndmask_b32_e32 v24, v24, v243, vcc
	ds_write_b32 v25, v24 offset:21504
	s_cmpk_eq_i32 s9, 0x7e0
	s_cbranch_scc1 .LBB0_1434
	s_mov_b32 s21, s24
	s_mov_b32 s20, s9
	s_branch .LBB0_1406
